# adaLN MOD inner loop software-pipelined (next k-block's 8 weight loads issued before the current FMAs); on top of rmw2
# speedup vs baseline: 1.0057x; 1.0057x over previous
; #define LAS __attribute__((address_space(3)))
; __device__ __forceinline__ void p0_prologue(const Frame& F0, const Args& a0) {
;     ...
;         for (int unit = F.vcu; unit < DEPTH * (D6 / 64); unit += F.G) {
;             const int l = unit / (D6 / 64), n0 = (unit % (D6 / 64)) * 64, kp = F.lane >> 4, nq = F.lane & 15;
;             const float* w = a.in[I_WADA] + ((size_t)l * DM + F.wave * 256 + kp) * D6 + n0 + 4 * nq;
;             const LAS float* s = sc + F.wave * 256 + kp;
;             f32x4 a0 = (f32x4){0.f, 0.f, 0.f, 0.f}, a1 = a0, a2 = a0, a3 = a0, a4 = a0;
; #pragma unroll 8
;             for (int k = 0; k < 64; ++k) { const f32x4 wv = *(const f32x4*)(w + (size_t)(4 * k) * D6); a0 += wv * s[4 * k]; a1 += wv * s[DM + 4 * k]; a2 += wv * s[2 * DM + 4 * k]; a3 += wv * s[3 * DM + 4 * k]; a4 += wv * s[4 * DM + 4 * k]; }
.LBB0_103:
	s_mul_hi_i32 s4, s14, 0x2aaaaaab
	s_lshr_b32 s5, s4, 31
	s_ashr_i32 s4, s4, 5
	s_add_i32 s6, s4, s5
	s_mul_i32 s4, s6, 0xc0
	s_sub_i32 s4, s14, s4
	s_ashr_i32 s7, s6, 31
	s_lshl_b32 s8, s4, 6
	s_lshl_b64 s[4:5], s[6:7], 11
	v_lshl_add_u64 v[8:9], v[2:3], 0, s[4:5]
	v_mad_u64_u32 v[10:11], s[4:5], v8, s21, v[6:7]
	v_mad_i32_i24 v11, v9, s21, v11
	s_ashr_i32 s9, s8, 31
	v_lshl_add_u64 v[8:9], s[8:9], 2, v[10:11]
	v_lshl_add_u64 v[14:15], v[8:9], 0, v[4:5]
	s_mov_b64 s[12:13], 0
	v_mov_b32_e32 v36, v1
	v_mov_b32_e32 v20, 0
	v_mov_b32_e32 v21, v5
	v_mov_b32_e32 v8, 0
	v_mov_b32_e32 v9, v5
	v_mov_b32_e32 v22, 0
	v_mov_b32_e32 v23, v5
	v_mov_b32_e32 v10, 0
	v_mov_b32_e32 v11, v5
	s_waitcnt vmcnt(1)
	v_mov_b32_e32 v24, 0
	v_mov_b32_e32 v25, v5
	v_mov_b32_e32 v12, 0
	v_mov_b32_e32 v13, v5
	v_mov_b32_e32 v26, 0
	v_mov_b32_e32 v27, v5
	v_mov_b32_e32 v16, 0
	v_mov_b32_e32 v17, v5
	s_waitcnt vmcnt(0)
	v_mov_b32_e32 v28, 0
	v_mov_b32_e32 v29, v5
	v_mov_b32_e32 v18, 0
	v_mov_b32_e32 v19, v5
	v_lshl_add_u64 v[192:193], v[14:15], 0, s[12:13]
	v_add_co_u32_e64 v42, s[4:5], s22, v192
	s_nop 1
	v_addc_co_u32_e64 v43, s[4:5], 0, v193, s[4:5]
	v_add_co_u32_e64 v52, s[4:5], s23, v192
	s_nop 1
	v_addc_co_u32_e64 v53, s[4:5], 0, v193, s[4:5]
	global_load_dwordx4 v[38:41], v[192:193], off nt
	v_add_co_u32_e64 v56, s[4:5], s24, v192
	s_nop 1
	v_addc_co_u32_e64 v57, s[4:5], 0, v193, s[4:5]
	v_add_co_u32_e64 v60, s[4:5], s25, v192
	s_nop 1
	v_addc_co_u32_e64 v61, s[4:5], 0, v193, s[4:5]
	v_add_co_u32_e64 v64, s[4:5], s26, v192
	s_nop 1
	v_addc_co_u32_e64 v65, s[4:5], 0, v193, s[4:5]
	v_add_co_u32_e64 v68, s[4:5], s27, v192
	s_nop 1
	v_addc_co_u32_e64 v69, s[4:5], 0, v193, s[4:5]
	v_add_co_u32_e64 v196, s[4:5], s28, v192
	s_nop 1
	v_addc_co_u32_e64 v197, s[4:5], 0, v193, s[4:5]
	global_load_dwordx4 v[42:45], v[42:43], off nt
	s_nop 0
	global_load_dwordx4 v[52:55], v[52:53], off nt
	s_nop 0
	global_load_dwordx4 v[56:59], v[56:57], off nt
	s_nop 0
	global_load_dwordx4 v[60:63], v[60:61], off nt
	s_nop 0
	global_load_dwordx4 v[64:67], v[64:65], off nt
	s_nop 0
	global_load_dwordx4 v[68:71], v[68:69], off nt
	s_nop 0
	global_load_dwordx4 v[72:75], v[196:197], off nt
.LBB0_104:
	ds_read2_b32 v[32:33], v36 offset1:4
	ds_read2_b32 v[30:31], v36 offset0:8 offset1:12
	ds_read2_b32 v[46:47], v36 offset0:16 offset1:20
	ds_read2_b32 v[76:77], v36 offset0:24 offset1:28
	v_add_u32_e32 v37, 0x2000, v36
	v_add_u32_e32 v194, 0x4000, v36
	v_add_u32_e32 v195, 0x6000, v36
	v_add_u32_e32 v51, 0x8000, v36
	ds_read2_b32 v[78:79], v37 offset1:4
	ds_read2_b32 v[80:81], v194 offset1:4
	ds_read2_b32 v[82:83], v195 offset1:4
	ds_read2_b32 v[84:85], v51 offset1:4
	ds_read2_b32 v[86:87], v37 offset0:8 offset1:12
	ds_read2_b32 v[88:89], v194 offset0:8 offset1:12
	ds_read2_b32 v[90:91], v195 offset0:8 offset1:12
	ds_read2_b32 v[92:93], v51 offset0:8 offset1:12
	ds_read2_b32 v[94:95], v37 offset0:16 offset1:20
	ds_read2_b32 v[96:97], v194 offset0:16 offset1:20
	ds_read2_b32 v[98:99], v195 offset0:16 offset1:20
	ds_read2_b32 v[100:101], v51 offset0:16 offset1:20
	ds_read2_b32 v[102:103], v37 offset0:24 offset1:28
	ds_read2_b32 v[104:105], v194 offset0:24 offset1:28
	ds_read2_b32 v[106:107], v195 offset0:24 offset1:28
	ds_read2_b32 v[108:109], v51 offset0:24 offset1:28
	s_waitcnt lgkmcnt(14)
	v_mov_b32_e32 v34, v33
	v_mov_b32_e32 v116, v79
	v_mov_b32_e32 v118, v81
	s_waitcnt lgkmcnt(13)
	v_mov_b32_e32 v120, v83
	s_waitcnt lgkmcnt(12)
	v_mov_b32_e32 v122, v85
	v_mov_b32_e32 v110, v31
	s_waitcnt lgkmcnt(11)
	v_mov_b32_e32 v124, v87
	s_waitcnt lgkmcnt(10)
	v_mov_b32_e32 v126, v89
	s_waitcnt lgkmcnt(9)
	v_mov_b32_e32 v128, v91
	s_waitcnt lgkmcnt(8)
	v_mov_b32_e32 v130, v93
	v_mov_b32_e32 v112, v47
	s_waitcnt lgkmcnt(7)
	v_mov_b32_e32 v132, v95
	s_waitcnt lgkmcnt(6)
	v_mov_b32_e32 v134, v97
	s_waitcnt lgkmcnt(5)
	v_mov_b32_e32 v136, v99
	s_waitcnt lgkmcnt(4)
	v_mov_b32_e32 v138, v101
	s_add_u32 s12, s12, 0x180000
	s_addc_u32 s13, s13, 0
	v_mov_b32_e32 v114, v77
	s_waitcnt lgkmcnt(3)
	v_mov_b32_e32 v140, v103
	s_waitcnt lgkmcnt(2)
	v_mov_b32_e32 v142, v105
	s_waitcnt lgkmcnt(1)
	v_mov_b32_e32 v144, v107
	s_waitcnt lgkmcnt(0)
	v_mov_b32_e32 v146, v109
	v_add_u32_e32 v36, 0x80, v36
	s_waitcnt vmcnt(0)
	v_mov_b64_e32 v[160:161], v[38:39]
	v_mov_b64_e32 v[162:163], v[40:41]
	v_mov_b64_e32 v[164:165], v[42:43]
	v_mov_b64_e32 v[166:167], v[44:45]
	v_mov_b64_e32 v[168:169], v[52:53]
	v_mov_b64_e32 v[170:171], v[54:55]
	v_mov_b64_e32 v[172:173], v[56:57]
	v_mov_b64_e32 v[174:175], v[58:59]
	v_mov_b64_e32 v[176:177], v[60:61]
	v_mov_b64_e32 v[178:179], v[62:63]
	v_mov_b64_e32 v[180:181], v[64:65]
	v_mov_b64_e32 v[182:183], v[66:67]
	v_mov_b64_e32 v[184:185], v[68:69]
	v_mov_b64_e32 v[186:187], v[70:71]
	v_mov_b64_e32 v[188:189], v[72:73]
	v_mov_b64_e32 v[190:191], v[74:75]
	s_cmp_eq_u32 s12, 0xc00000
	s_cbranch_scc1 .Lmy_mod_last
	v_lshl_add_u64 v[192:193], v[14:15], 0, s[12:13]
	v_add_co_u32_e64 v42, s[4:5], s22, v192
	s_nop 1
	v_addc_co_u32_e64 v43, s[4:5], 0, v193, s[4:5]
	v_add_co_u32_e64 v52, s[4:5], s23, v192
	s_nop 1
	v_addc_co_u32_e64 v53, s[4:5], 0, v193, s[4:5]
	global_load_dwordx4 v[38:41], v[192:193], off nt
	v_add_co_u32_e64 v56, s[4:5], s24, v192
	s_nop 1
	v_addc_co_u32_e64 v57, s[4:5], 0, v193, s[4:5]
	v_add_co_u32_e64 v60, s[4:5], s25, v192
	s_nop 1
	v_addc_co_u32_e64 v61, s[4:5], 0, v193, s[4:5]
	v_add_co_u32_e64 v64, s[4:5], s26, v192
	s_nop 1
	v_addc_co_u32_e64 v65, s[4:5], 0, v193, s[4:5]
	v_add_co_u32_e64 v68, s[4:5], s27, v192
	s_nop 1
	v_addc_co_u32_e64 v69, s[4:5], 0, v193, s[4:5]
	v_add_co_u32_e64 v196, s[4:5], s28, v192
	s_nop 1
	v_addc_co_u32_e64 v197, s[4:5], 0, v193, s[4:5]
	global_load_dwordx4 v[42:45], v[42:43], off nt
	s_nop 0
	global_load_dwordx4 v[52:55], v[52:53], off nt
	s_nop 0
	global_load_dwordx4 v[56:59], v[56:57], off nt
	s_nop 0
	global_load_dwordx4 v[60:63], v[60:61], off nt
	s_nop 0
	global_load_dwordx4 v[64:67], v[64:65], off nt
	s_nop 0
	global_load_dwordx4 v[68:71], v[68:69], off nt
	s_nop 0
	global_load_dwordx4 v[72:75], v[196:197], off nt
; __device__ __forceinline__ void p0_prologue(const Frame& F0, const Args& a0) {
;     ...
;             for (int k = 0; k < 64; ++k) { const f32x4 wv = *(const f32x4*)(w + (size_t)(4 * k) * D6); a0 += wv * s[4 * k]; a1 += wv * s[DM + 4 * k]; a2 += wv * s[2 * DM + 4 * k]; a3 += wv * s[3 * DM + 4 * k]; a4 += wv * s[4 * DM + 4 * k]; }
.Lmy_mod_last:
	v_pk_fma_f32 v[28:29], v[160:161], v[32:33], v[28:29] op_sel_hi:[1,0,1]
	v_pk_fma_f32 v[18:19], v[162:163], v[32:33], v[18:19] op_sel_hi:[1,0,1]
	v_pk_fma_f32 v[26:27], v[160:161], v[78:79], v[26:27] op_sel_hi:[1,0,1]
	v_pk_fma_f32 v[16:17], v[162:163], v[78:79], v[16:17] op_sel_hi:[1,0,1]
	v_pk_fma_f32 v[24:25], v[160:161], v[80:81], v[24:25] op_sel_hi:[1,0,1]
	v_pk_fma_f32 v[12:13], v[162:163], v[80:81], v[12:13] op_sel_hi:[1,0,1]
	v_pk_fma_f32 v[22:23], v[160:161], v[82:83], v[22:23] op_sel_hi:[1,0,1]
	v_pk_fma_f32 v[10:11], v[162:163], v[82:83], v[10:11] op_sel_hi:[1,0,1]
	v_pk_fma_f32 v[20:21], v[160:161], v[84:85], v[20:21] op_sel_hi:[1,0,1]
	v_pk_fma_f32 v[8:9], v[162:163], v[84:85], v[8:9] op_sel_hi:[1,0,1]
	v_pk_fma_f32 v[28:29], v[164:165], v[34:35], v[28:29] op_sel_hi:[1,0,1]
	v_pk_fma_f32 v[18:19], v[166:167], v[34:35], v[18:19] op_sel_hi:[1,0,1]
	v_pk_fma_f32 v[26:27], v[164:165], v[116:117], v[26:27] op_sel_hi:[1,0,1]
	v_pk_fma_f32 v[16:17], v[166:167], v[116:117], v[16:17] op_sel_hi:[1,0,1]
	v_pk_fma_f32 v[24:25], v[164:165], v[118:119], v[24:25] op_sel_hi:[1,0,1]
	v_pk_fma_f32 v[12:13], v[166:167], v[118:119], v[12:13] op_sel_hi:[1,0,1]
	v_pk_fma_f32 v[22:23], v[164:165], v[120:121], v[22:23] op_sel_hi:[1,0,1]
	v_pk_fma_f32 v[10:11], v[166:167], v[120:121], v[10:11] op_sel_hi:[1,0,1]
	v_pk_fma_f32 v[20:21], v[164:165], v[122:123], v[20:21] op_sel_hi:[1,0,1]
	v_pk_fma_f32 v[8:9], v[166:167], v[122:123], v[8:9] op_sel_hi:[1,0,1]
	v_pk_fma_f32 v[18:19], v[170:171], v[30:31], v[18:19] op_sel_hi:[1,0,1]
	v_pk_fma_f32 v[28:29], v[168:169], v[30:31], v[28:29] op_sel_hi:[1,0,1]
	v_pk_fma_f32 v[16:17], v[170:171], v[86:87], v[16:17] op_sel_hi:[1,0,1]
	v_pk_fma_f32 v[26:27], v[168:169], v[86:87], v[26:27] op_sel_hi:[1,0,1]
	v_pk_fma_f32 v[12:13], v[170:171], v[88:89], v[12:13] op_sel_hi:[1,0,1]
	v_pk_fma_f32 v[24:25], v[168:169], v[88:89], v[24:25] op_sel_hi:[1,0,1]
	v_pk_fma_f32 v[10:11], v[170:171], v[90:91], v[10:11] op_sel_hi:[1,0,1]
	v_pk_fma_f32 v[22:23], v[168:169], v[90:91], v[22:23] op_sel_hi:[1,0,1]
	v_pk_fma_f32 v[8:9], v[170:171], v[92:93], v[8:9] op_sel_hi:[1,0,1]
	v_pk_fma_f32 v[20:21], v[168:169], v[92:93], v[20:21] op_sel_hi:[1,0,1]
	v_pk_fma_f32 v[18:19], v[174:175], v[110:111], v[18:19] op_sel_hi:[1,0,1]
	v_pk_fma_f32 v[28:29], v[172:173], v[110:111], v[28:29] op_sel_hi:[1,0,1]
	v_pk_fma_f32 v[16:17], v[174:175], v[124:125], v[16:17] op_sel_hi:[1,0,1]
	v_pk_fma_f32 v[26:27], v[172:173], v[124:125], v[26:27] op_sel_hi:[1,0,1]
	v_pk_fma_f32 v[12:13], v[174:175], v[126:127], v[12:13] op_sel_hi:[1,0,1]
	v_pk_fma_f32 v[24:25], v[172:173], v[126:127], v[24:25] op_sel_hi:[1,0,1]
	v_pk_fma_f32 v[10:11], v[174:175], v[128:129], v[10:11] op_sel_hi:[1,0,1]
	v_pk_fma_f32 v[22:23], v[172:173], v[128:129], v[22:23] op_sel_hi:[1,0,1]
	v_pk_fma_f32 v[8:9], v[174:175], v[130:131], v[8:9] op_sel_hi:[1,0,1]
	v_pk_fma_f32 v[20:21], v[172:173], v[130:131], v[20:21] op_sel_hi:[1,0,1]
	v_pk_fma_f32 v[18:19], v[178:179], v[46:47], v[18:19] op_sel_hi:[1,0,1]
	v_pk_fma_f32 v[28:29], v[176:177], v[46:47], v[28:29] op_sel_hi:[1,0,1]
	v_pk_fma_f32 v[16:17], v[178:179], v[94:95], v[16:17] op_sel_hi:[1,0,1]
	v_pk_fma_f32 v[26:27], v[176:177], v[94:95], v[26:27] op_sel_hi:[1,0,1]
	v_pk_fma_f32 v[12:13], v[178:179], v[96:97], v[12:13] op_sel_hi:[1,0,1]
	v_pk_fma_f32 v[24:25], v[176:177], v[96:97], v[24:25] op_sel_hi:[1,0,1]
	v_pk_fma_f32 v[10:11], v[178:179], v[98:99], v[10:11] op_sel_hi:[1,0,1]
	v_pk_fma_f32 v[22:23], v[176:177], v[98:99], v[22:23] op_sel_hi:[1,0,1]
	v_pk_fma_f32 v[8:9], v[178:179], v[100:101], v[8:9] op_sel_hi:[1,0,1]
	v_pk_fma_f32 v[20:21], v[176:177], v[100:101], v[20:21] op_sel_hi:[1,0,1]
	v_pk_fma_f32 v[18:19], v[182:183], v[112:113], v[18:19] op_sel_hi:[1,0,1]
	v_pk_fma_f32 v[28:29], v[180:181], v[112:113], v[28:29] op_sel_hi:[1,0,1]
	v_pk_fma_f32 v[16:17], v[182:183], v[132:133], v[16:17] op_sel_hi:[1,0,1]
	v_pk_fma_f32 v[26:27], v[180:181], v[132:133], v[26:27] op_sel_hi:[1,0,1]
	v_pk_fma_f32 v[12:13], v[182:183], v[134:135], v[12:13] op_sel_hi:[1,0,1]
	v_pk_fma_f32 v[24:25], v[180:181], v[134:135], v[24:25] op_sel_hi:[1,0,1]
	v_pk_fma_f32 v[10:11], v[182:183], v[136:137], v[10:11] op_sel_hi:[1,0,1]
	v_pk_fma_f32 v[22:23], v[180:181], v[136:137], v[22:23] op_sel_hi:[1,0,1]
	v_pk_fma_f32 v[8:9], v[182:183], v[138:139], v[8:9] op_sel_hi:[1,0,1]
	v_pk_fma_f32 v[20:21], v[180:181], v[138:139], v[20:21] op_sel_hi:[1,0,1]
	v_pk_fma_f32 v[18:19], v[186:187], v[76:77], v[18:19] op_sel_hi:[1,0,1]
	v_pk_fma_f32 v[28:29], v[184:185], v[76:77], v[28:29] op_sel_hi:[1,0,1]
	v_pk_fma_f32 v[16:17], v[186:187], v[102:103], v[16:17] op_sel_hi:[1,0,1]
	v_pk_fma_f32 v[26:27], v[184:185], v[102:103], v[26:27] op_sel_hi:[1,0,1]
	v_pk_fma_f32 v[12:13], v[186:187], v[104:105], v[12:13] op_sel_hi:[1,0,1]
	v_pk_fma_f32 v[24:25], v[184:185], v[104:105], v[24:25] op_sel_hi:[1,0,1]
	v_pk_fma_f32 v[10:11], v[186:187], v[106:107], v[10:11] op_sel_hi:[1,0,1]
	v_pk_fma_f32 v[22:23], v[184:185], v[106:107], v[22:23] op_sel_hi:[1,0,1]
	v_pk_fma_f32 v[8:9], v[186:187], v[108:109], v[8:9] op_sel_hi:[1,0,1]
	v_pk_fma_f32 v[20:21], v[184:185], v[108:109], v[20:21] op_sel_hi:[1,0,1]
	v_pk_fma_f32 v[18:19], v[190:191], v[114:115], v[18:19] op_sel_hi:[1,0,1]
	v_pk_fma_f32 v[28:29], v[188:189], v[114:115], v[28:29] op_sel_hi:[1,0,1]
	v_pk_fma_f32 v[16:17], v[190:191], v[140:141], v[16:17] op_sel_hi:[1,0,1]
	v_pk_fma_f32 v[26:27], v[188:189], v[140:141], v[26:27] op_sel_hi:[1,0,1]
	v_pk_fma_f32 v[12:13], v[190:191], v[142:143], v[12:13] op_sel_hi:[1,0,1]
	v_pk_fma_f32 v[24:25], v[188:189], v[142:143], v[24:25] op_sel_hi:[1,0,1]
	v_pk_fma_f32 v[10:11], v[190:191], v[144:145], v[10:11] op_sel_hi:[1,0,1]
	v_pk_fma_f32 v[22:23], v[188:189], v[144:145], v[22:23] op_sel_hi:[1,0,1]
	v_pk_fma_f32 v[8:9], v[190:191], v[146:147], v[8:9] op_sel_hi:[1,0,1]
	v_pk_fma_f32 v[20:21], v[188:189], v[146:147], v[20:21] op_sel_hi:[1,0,1]
	s_cmp_lg_u32 s12, 0xc00000
	s_cbranch_scc1 .LBB0_104
; #define LAS __attribute__((address_space(3)))
; __device__ __forceinline__ float shx(float v, int m, int lane) { return __builtin_bit_cast(float, __builtin_amdgcn_ds_bpermute((lane ^ m) << 2, __builtin_bit_cast(int, v))); }
; __device__ __forceinline__ void p0_prologue(const Frame& F0, const Args& a0) {
;     ...
;             for (int e = 0; e < 4; ++e) { a0[e] += shx(a0[e], 32, F.lane); a1[e] += shx(a1[e], 32, F.lane); a2[e] += shx(a2[e], 32, F.lane); a3[e] += shx(a3[e], 32, F.lane); a4[e] += shx(a4[e], 32, F.lane);
;                 a0[e] += shx(a0[e], 16, F.lane); a1[e] += shx(a1[e], 16, F.lane); a2[e] += shx(a2[e], 16, F.lane); a3[e] += shx(a3[e], 16, F.lane); a4[e] += shx(a4[e], 16, F.lane); }
;             if (kp == 0) { LAS f32x4* r4 = (LAS f32x4*)red + (F.wave * 5) * 16 + nq; r4[0] = a0; r4[16] = a1; r4[32] = a2; r4[48] = a3; r4[64] = a4; }
	ds_bpermute_b32 v14, v48, v28
	ds_bpermute_b32 v30, v48, v26
	ds_bpermute_b32 v15, v48, v29
	ds_bpermute_b32 v32, v48, v24
	ds_bpermute_b32 v34, v48, v22
	ds_bpermute_b32 v31, v48, v27
	ds_bpermute_b32 v36, v48, v20
	ds_bpermute_b32 v33, v48, v25
	ds_bpermute_b32 v35, v48, v23
	ds_bpermute_b32 v37, v48, v21
	ds_bpermute_b32 v38, v48, v18
	ds_bpermute_b32 v40, v48, v16
	ds_bpermute_b32 v39, v48, v19
	ds_bpermute_b32 v42, v48, v12
	ds_bpermute_b32 v44, v48, v10
	ds_bpermute_b32 v41, v48, v17
	ds_bpermute_b32 v46, v48, v8
	ds_bpermute_b32 v43, v48, v13
	ds_bpermute_b32 v45, v48, v11
	ds_bpermute_b32 v47, v48, v9
	s_waitcnt lgkmcnt(14)
	v_pk_add_f32 v[14:15], v[28:29], v[14:15]
	v_pk_add_f32 v[26:27], v[26:27], v[30:31]
	s_waitcnt lgkmcnt(12)
	v_pk_add_f32 v[24:25], v[24:25], v[32:33]
	s_waitcnt lgkmcnt(11)
	v_pk_add_f32 v[22:23], v[22:23], v[34:35]
	s_waitcnt lgkmcnt(10)
	v_pk_add_f32 v[20:21], v[20:21], v[36:37]
	s_waitcnt lgkmcnt(7)
	v_pk_add_f32 v[18:19], v[18:19], v[38:39]
	s_waitcnt lgkmcnt(4)
	v_pk_add_f32 v[16:17], v[16:17], v[40:41]
	s_waitcnt lgkmcnt(2)
	v_pk_add_f32 v[12:13], v[12:13], v[42:43]
	s_waitcnt lgkmcnt(1)
	v_pk_add_f32 v[10:11], v[10:11], v[44:45]
	s_waitcnt lgkmcnt(0)
	v_pk_add_f32 v[8:9], v[8:9], v[46:47]
	ds_bpermute_b32 v28, v49, v14
	ds_bpermute_b32 v30, v49, v26
	ds_bpermute_b32 v32, v49, v24
	ds_bpermute_b32 v34, v49, v22
	ds_bpermute_b32 v36, v49, v20
	ds_bpermute_b32 v29, v49, v15
	ds_bpermute_b32 v31, v49, v27
	ds_bpermute_b32 v33, v49, v25
	ds_bpermute_b32 v35, v49, v23
	ds_bpermute_b32 v37, v49, v21
	ds_bpermute_b32 v38, v49, v18
	ds_bpermute_b32 v40, v49, v16
	ds_bpermute_b32 v42, v49, v12
	ds_bpermute_b32 v44, v49, v10
	ds_bpermute_b32 v46, v49, v8
	ds_bpermute_b32 v39, v49, v19
	ds_bpermute_b32 v41, v49, v17
	ds_bpermute_b32 v43, v49, v13
	ds_bpermute_b32 v45, v49, v11
	ds_bpermute_b32 v47, v49, v9
	s_and_saveexec_b64 s[4:5], vcc
	s_cbranch_execz .LBB0_107
	s_waitcnt lgkmcnt(10)
	v_pk_add_f32 v[52:53], v[20:21], v[36:37]
	v_pk_add_f32 v[20:21], v[24:25], v[32:33]
	s_waitcnt lgkmcnt(3)
	v_pk_add_f32 v[32:33], v[16:17], v[40:41]
	v_pk_add_f32 v[16:17], v[18:19], v[38:39]
	v_pk_add_f32 v[14:15], v[14:15], v[28:29]
	s_waitcnt lgkmcnt(0)
	v_pk_add_f32 v[54:55], v[8:9], v[46:47]
	v_pk_add_f32 v[10:11], v[10:11], v[44:45]
	v_pk_add_f32 v[8:9], v[22:23], v[34:35]
	v_pk_add_f32 v[22:23], v[12:13], v[42:43]
	v_pk_add_f32 v[30:31], v[26:27], v[30:31]
	ds_write_b128 v50, v[14:17] offset:49152
	ds_write_b128 v50, v[30:33] offset:49408
	ds_write_b128 v50, v[20:23] offset:49664
	ds_write_b128 v50, v[8:11] offset:49920
	ds_write_b128 v50, v[52:55] offset:50176
